# MLA mid-barrier moved to middle of exp block (balanced stagger); cross-half max via v_permlane32_swap; fox QK K-fragments prefetched into free VGPRs (counted lgkmcnt)
# speedup vs baseline: 1.0118x; 1.0118x over previous
; #define MFMA(a, b, c) __builtin_amdgcn_mfma_f32_32x32x16_bf16((a), (b), (c), 0, 0, 0)
; DI float fexp2(float x) { return __builtin_amdgcn_exp2f(x); }
; template <int TYPE>
; DI void attn_item(KargPtr p, int b, int h, int qb, unsigned char* smem) {
;     ...
;     auto compute = [&](const int kt, const int buf) __attribute__((always_inline)) {
;         const unsigned char* kb = smem + buf * BUFB; const unsigned char* vb = kb + KBYTES;
;         const int k0 = kt * 64;
;         bool need;
;         if (TYPE == 0) {
;             if (!wdone && k0 <= qw + 31) wdone = (__all(qbound + *(const float*)(vb + VBYTES) - m < -150.f) != 0);
;             need = (k0 <= qw + 31) && !wdone;
;         }
;         else if (TYPE == 1) need = (k0 <= qw);
;         else need = (k0 <= qw + 30) && !wdone;
;         if (need) {
;             f32x16 s0, s1;
; #pragma unroll
;             for (int i = 0; i < 16; ++i) { s0[i] = 0.f; s1[i] = 0.f; }
; #pragma unroll
;             for (int ks = 0; ks < KS; ++ks) {
;                 const bf16x8 a0 = *(const bf16x8*)(kb + r * KROWB + ks * 32 + hh * 16);
;                 const bf16x8 a1 = *(const bf16x8*)(kb + (32 + r) * KROWB + ks * 32 + hh * 16);
;                 s0 = MFMA(a0, qfrag[ks], s0); s1 = MFMA(a1, qfrag[ks], s1);
;             }
;             if (TYPE != 2) {
;                 if (TYPE == 0) {
;                     if (k0 + 63 > qw) {
;                         asm volatile("");
;                         const int rel = myq - k0 - 4 * hh;
; #pragma unroll
;                         for (int i = 0; i < 16; ++i) {
;                             const int off = 8 * (i >> 2) + (i & 3);
;                             if (off > rel) s0[i] = -1e30f;
;                             if (off + 32 > rel) s1[i] = -1e30f;
;                         }
;                     }
;                 }
;                 float mx = s0[0];
; #pragma unroll
;                 for (int i = 1; i < 16; ++i) mx = fmaxf(mx, s0[i]);
; #pragma unroll
;                 for (int i = 0; i < 16; ++i) mx = fmaxf(mx, s1[i]);
;                 mx = fmaxf(mx, __shfl_xor(mx, 32));
;                 const float mnew = fmaxf(m, mx);
;                 const float alpha = fexp2(m - mnew);
.LBB0_591:
	s_add_i32 s18, s12, -3
	s_add_i32 s10, s12, -1
	s_cmp_lt_u32 s18, s14
	s_cselect_b32 s10, s10, s16
	s_lshl_b32 s84, s10, 6
	v_add_u32_e32 v36, s84, v134
	v_ashrrev_i32_e32 v37, 31, v36
	v_lshlrev_b64 v[36:37], 10, v[36:37]
	v_lshl_add_u64 v[36:37], s[6:7], 0, v[36:37]
	v_lshlrev_b32_e32 v2, 1, v132
	v_lshl_add_u64 v[36:37], v[36:37], 0, v[2:3]
	global_load_dwordx4 v[112:115], v[36:37], off
	v_add_u32_e32 v36, s84, v136
	v_ashrrev_i32_e32 v37, 31, v36
	v_lshlrev_b64 v[36:37], 10, v[36:37]
	s_lshl_b64 s[10:11], s[84:85], 7
	v_lshl_add_u64 v[36:37], s[6:7], 0, v[36:37]
	s_add_u32 s10, s8, s10
	v_lshl_add_u64 v[36:37], v[36:37], 0, v[2:3]
	s_addc_u32 s11, s9, s11
	global_load_dwordx4 v[116:119], v[36:37], off
	v_lshl_add_u64 v[36:37], v[154:155], 1, s[10:11]
	v_lshl_add_u64 v[36:37], v[36:37], 0, v[2:3]
	global_load_dwordx4 v[120:123], v[36:37], off
	v_lshl_add_u64 v[36:37], v[156:157], 1, s[10:11]
	v_lshl_add_u64 v[36:37], v[36:37], 0, v[2:3]
	global_load_dwordx4 v[124:127], v[36:37], off
	v_add_u32_e32 v36, s84, v158
	v_ashrrev_i32_e32 v37, 31, v36
	v_lshlrev_b64 v[36:37], 6, v[36:37]
	v_lshl_add_u64 v[36:37], s[4:5], 0, v[36:37]
	v_mov_b32_e32 v161, v3
	v_lshl_add_u64 v[36:37], v[36:37], 0, v[160:161]
	global_load_dwordx4 v[128:131], v[36:37], off
	s_sub_i32 s10, s17, 64
	v_cmp_le_i32_e32 vcc, s10, v176
	s_and_saveexec_b64 s[10:11], vcc
	s_cbranch_execz .Lmla_skip_a
	ds_read_b128 v[52:55], v183 offset:6656
	ds_read_b128 v[36:39], v183
	ds_read_b128 v[56:59], v183 offset:32
	ds_read_b128 v[138:141], v183 offset:6688
	s_waitcnt lgkmcnt(2)
	v_mfma_f32_32x32x16_bf16 v[36:51], v[36:39], v[68:71], 0
	s_waitcnt lgkmcnt(1)
	v_mfma_f32_32x32x16_bf16 v[36:51], v[56:59], v[72:75], v[36:51]
	ds_read_b128 v[56:59], v183 offset:64
	ds_read_b128 v[142:145], v183 offset:6720
	s_waitcnt lgkmcnt(1)
	v_mfma_f32_32x32x16_bf16 v[36:51], v[56:59], v[76:79], v[36:51]
	ds_read_b128 v[56:59], v183 offset:96
	ds_read_b128 v[150:153], v183 offset:6752
	s_waitcnt lgkmcnt(1)
	v_mfma_f32_32x32x16_bf16 v[36:51], v[56:59], v[80:83], v[36:51]
	ds_read_b128 v[56:59], v183 offset:128
	ds_read_b128 v[164:167], v183 offset:6784
	s_waitcnt lgkmcnt(1)
	v_mfma_f32_32x32x16_bf16 v[36:51], v[56:59], v[84:87], v[36:51]
	ds_read_b128 v[56:59], v183 offset:160
	ds_read_b128 v[168:171], v183 offset:6816
	s_waitcnt lgkmcnt(1)
	v_mfma_f32_32x32x16_bf16 v[36:51], v[56:59], v[88:91], v[36:51]
	s_nop 11
	v_max_f32_e32 v56, v37, v37
	v_max_f32_e32 v57, v36, v36
	v_max_f32_e32 v56, v57, v56
	v_max3_f32 v56, v56, v38, v39
	v_max3_f32 v56, v56, v40, v41
	v_max3_f32 v56, v56, v42, v43
	v_max3_f32 v56, v56, v44, v45
	v_max3_f32 v56, v56, v46, v47
	v_max3_f32 v56, v56, v48, v49
	v_max3_f32 v146, v56, v50, v51
	v_mfma_f32_32x32x16_bf16 v[52:67], v[52:55], v[68:71], 0
	v_mfma_f32_32x32x16_bf16 v[52:67], v[138:141], v[72:75], v[52:67]
	v_and_b32_e32 v140, 64, v205
	v_xor_b32_e32 v139, 32, v205
	v_add_u32_e32 v140, 64, v140
	v_cmp_lt_i32_e32 vcc, v139, v140
	s_nop 1
	v_cndmask_b32_e32 v139, v205, v139, vcc
	v_mfma_f32_32x32x16_bf16 v[52:67], v[142:145], v[76:79], v[52:67]
	v_lshlrev_b32_e32 v139, 2, v139
	v_mfma_f32_32x32x16_bf16 v[52:67], v[150:153], v[80:83], v[52:67]
	v_mfma_f32_32x32x16_bf16 v[52:67], v[164:167], v[84:87], v[52:67]
	s_waitcnt lgkmcnt(0)
	v_mfma_f32_32x32x16_bf16 v[52:67], v[168:171], v[88:91], v[52:67]
	s_nop 11
	v_max3_f32 v138, v146, v52, v53
	v_max3_f32 v138, v138, v54, v55
	v_max3_f32 v138, v138, v56, v57
	v_max3_f32 v138, v138, v58, v59
	v_max3_f32 v138, v138, v60, v61
	v_max3_f32 v138, v138, v62, v63
	v_max3_f32 v138, v138, v64, v65
	v_max3_f32 v138, v138, v66, v67
	v_mov_b32_e32 v139, v138
	v_mov_b32_e32 v225, v138
	s_nop 1
	v_permlane32_swap_b32_e32 v139, v225
	v_max3_f32 v162, v163, v139, v225
	v_pk_add_f32 v[36:37], v[36:37], v[162:163] op_sel_hi:[1,0] neg_lo:[0,1] neg_hi:[0,1]
	v_pk_add_f32 v[52:53], v[52:53], v[162:163] op_sel_hi:[1,0] neg_lo:[0,1] neg_hi:[0,1]
	v_exp_f32_e32 v165, v36
	v_exp_f32_e32 v169, v37
	v_pk_add_f32 v[36:37], v[38:39], v[162:163] op_sel_hi:[1,0] neg_lo:[0,1] neg_hi:[0,1]
	v_pk_add_f32 v[38:39], v[54:55], v[162:163] op_sel_hi:[1,0] neg_lo:[0,1] neg_hi:[0,1]
	v_exp_f32_e32 v167, v52
	v_exp_f32_e32 v171, v53
	v_exp_f32_e32 v164, v36
	v_exp_f32_e32 v168, v37
	v_exp_f32_e32 v166, v38
	v_exp_f32_e32 v170, v39
	v_pk_add_f32 v[44:45], v[44:45], v[162:163] op_sel_hi:[1,0] neg_lo:[0,1] neg_hi:[0,1]
	v_pk_add_f32 v[36:37], v[168:169], v[164:165]
	v_pk_add_f32 v[52:53], v[60:61], v[162:163] op_sel_hi:[1,0] neg_lo:[0,1] neg_hi:[0,1]
	v_pk_add_f32 v[38:39], v[170:171], v[166:167]
	v_pk_add_f32 v[54:55], v[62:63], v[162:163] op_sel_hi:[1,0] neg_lo:[0,1] neg_hi:[0,1]
	v_pk_add_f32 v[36:37], v[38:39], v[36:37]
	v_pk_add_f32 v[38:39], v[40:41], v[162:163] op_sel_hi:[1,0] neg_lo:[0,1] neg_hi:[0,1]
	v_pk_add_f32 v[40:41], v[56:57], v[162:163] op_sel_hi:[1,0] neg_lo:[0,1] neg_hi:[0,1]
	v_exp_f32_e32 v173, v38
	v_exp_f32_e32 v175, v39
	v_exp_f32_e32 v172, v40
	v_exp_f32_e32 v174, v41
	v_pk_add_f32 v[40:41], v[42:43], v[162:163] op_sel_hi:[1,0] neg_lo:[0,1] neg_hi:[0,1]
	v_pk_add_f32 v[42:43], v[58:59], v[162:163] op_sel_hi:[1,0] neg_lo:[0,1] neg_hi:[0,1]
	v_add_f32_e32 v37, 0, v37
	v_pk_add_f32 v[38:39], v[174:175], v[172:173]
	v_exp_f32_e32 v139, v40
	v_pk_add_f32 v[38:39], v[38:39], v[38:39] op_sel_hi:[0,1]
	v_exp_f32_e32 v140, v41
	v_exp_f32_e32 v141, v42
	v_exp_f32_e32 v142, v43
	s_barrier
; template <int TYPE>
; DI void attn_item(KargPtr p, int b, int h, int qb, unsigned char* smem) {
;     ...
;                 for (int i = 0; i < 16; i += 2) {
;                     const f32x2_t mm = {mnew, mnew};
;                     const f32x2_t d0 = (f32x2_t){s0[i], s0[i + 1]} - mm, d1 = (f32x2_t){s1[i], s1[i + 1]} - mm;
;                     s0[i] = fexp2(d0[0]); s0[i + 1] = fexp2(d0[1]); s1[i] = fexp2(d1[0]); s1[i + 1] = fexp2(d1[1]);
;                     ps += (s0[i] + s0[i + 1]) + (s1[i] + s1[i + 1]);
;                 }
;                 lsum = lsum * alpha + ps;
; #pragma unroll
;                 for (int i = 0; i < 16; ++i) { o0[i] *= alpha; o1[i] *= alpha; }
;     ...
; #pragma unroll
;             for (int s2 = 0; s2 < 2; ++s2) {
;                 unsigned pk0[4], pk1[4];
; #pragma unroll
;                 for (int j = 0; j < 4; ++j) { pk0[j] = pack_bf16(s0[8 * s2 + 2 * j], s0[8 * s2 + 2 * j + 1]); pk1[j] = pack_bf16(s1[8 * s2 + 2 * j], s1[8 * s2 + 2 * j + 1]); }
;                 const uint4 u0 = make_uint4(pk0[0], pk0[1], pk0[2], pk0[3]), u1 = make_uint4(pk1[0], pk1[1], pk1[2], pk1[3]);
;                 const bf16x8 pf0 = __builtin_bit_cast(bf16x8, u0), pf1 = __builtin_bit_cast(bf16x8, u1);
;                 const bf16x8 v00 = *(const bf16x8*)(vb + r * VROWB + (16 * s2 + 8 * hh) * 2);
;                 const bf16x8 v01 = *(const bf16x8*)(vb + (32 + r) * VROWB + (16 * s2 + 8 * hh) * 2);
;                 const bf16x8 v10 = *(const bf16x8*)(vb + r * VROWB + (32 + 16 * s2 + 8 * hh) * 2);
;                 const bf16x8 v11 = *(const bf16x8*)(vb + (32 + r) * VROWB + (32 + 16 * s2 + 8 * hh) * 2);
;                 o0 = MFMA(v00, pf0, o0); o1 = MFMA(v01, pf0, o1);
;                 o0 = MFMA(v10, pf1, o0); o1 = MFMA(v11, pf1, o1);
;             }
;         }
;     };
;     ...
;     __syncthreads();
;     if (TYPE != 1 && tid < 16) flags[tid] = 0;
;     LOAD_TILE(A, TILE_OF(0));
;     WAIT_ALL(A);
;     STORE_TILE(A, 0);
;     LOAD_TILE(A, TILE_OF(1));
;     __syncthreads();
;     for (int n = 0; n < ntiles; n += 2) {
;         LOAD_TILE(B, TILE_OF(n + 2));
;         __builtin_amdgcn_sched_barrier(0);
;         compute(TILE_OF(n), 0);
;         __builtin_amdgcn_sched_barrier(0);
;         WAIT_OLD(A);
;         STORE_TILE(A, 1);
;         SB_FLAGS(n);
;         __syncthreads();
;         if (SB_DONE(n)) break;
;         if (n + 1 >= ntiles) break;
	v_add_f32_e32 v37, v36, v37
	v_exp_f32_e32 v36, v44
	v_exp_f32_e32 v38, v45
	v_exp_f32_e32 v40, v52
	v_exp_f32_e32 v42, v53
	v_add_f32_e32 v41, v140, v139
	v_add_f32_e32 v43, v142, v141
	v_pk_add_f32 v[44:45], v[38:39], v[36:37]
	v_pk_add_f32 v[52:53], v[42:43], v[40:41]
	v_pk_add_f32 v[48:49], v[48:49], v[162:163] op_sel_hi:[1,0] neg_lo:[0,1] neg_hi:[0,1]
	v_pk_add_f32 v[44:45], v[52:53], v[44:45]
	v_pk_add_f32 v[52:53], v[46:47], v[162:163] op_sel_hi:[1,0] neg_lo:[0,1] neg_hi:[0,1]
	v_exp_f32_e32 v46, v54
	v_exp_f32_e32 v47, v52
	v_exp_f32_e32 v53, v53
	v_exp_f32_e32 v52, v55
	v_pk_add_f32 v[56:57], v[64:65], v[162:163] op_sel_hi:[1,0] neg_lo:[0,1] neg_hi:[0,1]
	v_pk_add_f32 v[44:45], v[44:45], v[44:45] op_sel_hi:[0,1]
	v_exp_f32_e32 v41, v48
	v_pk_add_f32 v[54:55], v[52:53], v[46:47]
	v_exp_f32_e32 v43, v49
	v_pk_add_f32 v[54:55], v[54:55], v[54:55] op_sel_hi:[0,1]
	v_exp_f32_e32 v146, v56
	v_exp_f32_e32 v147, v57
	v_pk_add_f32 v[50:51], v[50:51], v[162:163] op_sel_hi:[1,0] neg_lo:[0,1] neg_hi:[0,1]
	v_pk_add_f32 v[58:59], v[66:67], v[162:163] op_sel_hi:[1,0] neg_lo:[0,1] neg_hi:[0,1]
	v_exp_f32_e32 v44, v50
	v_exp_f32_e32 v54, v51
	v_exp_f32_e32 v48, v58
	v_exp_f32_e32 v56, v59
	v_add_f32_e32 v49, v43, v41
	v_add_f32_e32 v57, v147, v146
	v_pk_add_f32 v[50:51], v[54:55], v[44:45]
	v_pk_add_f32 v[58:59], v[56:57], v[48:49]
	v_sub_f32_e32 v138, v163, v162
	v_pk_add_f32 v[50:51], v[58:59], v[50:51]
	v_cvt_pk_bf16_f32 v58, v165, v169
	v_add_f32_e32 v37, v50, v51
	v_exp_f32_e32 v50, v138
	v_cvt_pk_bf16_f32 v62, v167, v171
	v_cvt_pk_bf16_f32 v59, v164, v168
	v_cvt_pk_bf16_f32 v63, v166, v170
	v_cvt_pk_bf16_f32 v61, v139, v140
	v_cvt_pk_bf16_f32 v65, v141, v142
	ds_read_b128 v[138:141], v184 offset:17920
	ds_read_b128 v[142:145], v184 offset:13376
	ds_read_b128 v[150:153], v184 offset:17984
	ds_read_b128 v[164:167], v184 offset:13312
	ds_read_b128 v[168:171], v184 offset:13344
	v_pk_mul_f32 v[34:35], v[34:35], v[50:51] op_sel_hi:[1,0]
	v_pk_mul_f32 v[32:33], v[32:33], v[50:51] op_sel_hi:[1,0]
	v_pk_mul_f32 v[30:31], v[30:31], v[50:51] op_sel_hi:[1,0]
	v_pk_mul_f32 v[28:29], v[28:29], v[50:51] op_sel_hi:[1,0]
	v_pk_mul_f32 v[26:27], v[26:27], v[50:51] op_sel_hi:[1,0]
	v_pk_mul_f32 v[24:25], v[24:25], v[50:51] op_sel_hi:[1,0]
	v_pk_mul_f32 v[22:23], v[22:23], v[50:51] op_sel_hi:[1,0]
	v_pk_mul_f32 v[20:21], v[20:21], v[50:51] op_sel_hi:[1,0]
	v_pk_mul_f32 v[18:19], v[18:19], v[50:51] op_sel_hi:[1,0]
	v_pk_mul_f32 v[16:17], v[16:17], v[50:51] op_sel_hi:[1,0]
	v_pk_mul_f32 v[14:15], v[14:15], v[50:51] op_sel_hi:[1,0]
	v_pk_mul_f32 v[12:13], v[12:13], v[50:51] op_sel_hi:[1,0]
	v_pk_mul_f32 v[10:11], v[10:11], v[50:51] op_sel_hi:[1,0]
	v_pk_mul_f32 v[8:9], v[8:9], v[50:51] op_sel_hi:[1,0]
	v_pk_mul_f32 v[6:7], v[6:7], v[50:51] op_sel_hi:[1,0]
	v_pk_mul_f32 v[4:5], v[4:5], v[50:51] op_sel_hi:[1,0]
	v_cvt_pk_bf16_f32 v60, v173, v175
	v_cvt_pk_bf16_f32 v64, v172, v174
	v_fmac_f32_e32 v37, v185, v50
	s_waitcnt lgkmcnt(1)
	v_mfma_f32_32x32x16_bf16 v[20:35], v[164:167], v[58:61], v[20:35]
	v_cvt_pk_bf16_f32 v50, v40, v42
	v_cvt_pk_bf16_f32 v39, v47, v53
	v_cvt_pk_bf16_f32 v51, v46, v52
	v_cvt_pk_bf16_f32 v40, v41, v43
	v_cvt_pk_bf16_f32 v41, v44, v54
	v_cvt_pk_bf16_f32 v53, v48, v56
	ds_read_b128 v[42:45], v184 offset:17952
	ds_read_b128 v[46:49], v184 offset:13408
	ds_read_b128 v[54:57], v184 offset:18016
	v_mfma_f32_32x32x16_bf16 v[4:19], v[138:141], v[58:61], v[4:19]
	v_cvt_pk_bf16_f32 v38, v36, v38
	v_cvt_pk_bf16_f32 v52, v146, v147
	v_mov_b32_e32 v185, v37
	v_mov_b32_e32 v163, v162
	v_mfma_f32_32x32x16_bf16 v[20:35], v[142:145], v[62:65], v[20:35]
	v_mfma_f32_32x32x16_bf16 v[4:19], v[150:153], v[62:65], v[4:19]
	s_waitcnt lgkmcnt(3)
	v_mfma_f32_32x32x16_bf16 v[20:35], v[168:171], v[38:41], v[20:35]
	s_waitcnt lgkmcnt(2)
	v_mfma_f32_32x32x16_bf16 v[4:19], v[42:45], v[38:41], v[4:19]
	s_waitcnt lgkmcnt(1)
	v_mfma_f32_32x32x16_bf16 v[20:35], v[46:49], v[50:53], v[20:35]
	s_waitcnt lgkmcnt(0)
	v_mfma_f32_32x32x16_bf16 v[4:19], v[54:57], v[50:53], v[4:19]
.LBB0_593:
	s_or_b64 exec, exec, s[10:11]
	s_cmp_lt_u32 s12, s15
	s_waitcnt vmcnt(5)
	v_add_u32_e32 v36, 0x8800, v177
	s_cselect_b32 s10, s12, s16
	ds_write_b128 v137, v[92:95] offset:22784
	ds_write_b128 v159, v[96:99] offset:22784
	ds_write2_b64 v36, v[100:101], v[102:103] offset0:160 offset1:162
	v_add_u32_e32 v36, 0x8800, v179
	s_lshl_b32 s84, s10, 6
	ds_write2_b64 v36, v[104:105], v[106:107] offset0:160 offset1:162
	ds_write_b128 v181, v[108:111] offset:22912
	v_add_u32_e32 v36, s84, v134
	v_ashrrev_i32_e32 v37, 31, v36
	v_lshlrev_b64 v[36:37], 10, v[36:37]
	v_lshl_add_u64 v[36:37], s[6:7], 0, v[36:37]
	v_lshl_add_u64 v[36:37], v[36:37], 0, v[2:3]
	s_waitcnt lgkmcnt(0)
	s_barrier
	global_load_dwordx4 v[92:95], v[36:37], off
	v_add_u32_e32 v36, s84, v136
	v_ashrrev_i32_e32 v37, 31, v36
	v_lshlrev_b64 v[36:37], 10, v[36:37]
	s_lshl_b64 s[10:11], s[84:85], 7
	v_lshl_add_u64 v[36:37], s[6:7], 0, v[36:37]
	s_add_u32 s10, s8, s10
	v_lshl_add_u64 v[36:37], v[36:37], 0, v[2:3]
	s_addc_u32 s11, s9, s11
	global_load_dwordx4 v[96:99], v[36:37], off
	v_lshl_add_u64 v[36:37], v[154:155], 1, s[10:11]
	v_lshl_add_u64 v[36:37], v[36:37], 0, v[2:3]
	global_load_dwordx4 v[100:103], v[36:37], off
	v_lshl_add_u64 v[36:37], v[156:157], 1, s[10:11]
	v_lshl_add_u64 v[36:37], v[36:37], 0, v[2:3]
	global_load_dwordx4 v[104:107], v[36:37], off
	v_add_u32_e32 v36, s84, v158
	v_ashrrev_i32_e32 v37, 31, v36
	v_lshlrev_b64 v[36:37], 6, v[36:37]
	v_lshl_add_u64 v[36:37], s[4:5], 0, v[36:37]
	v_lshl_add_u64 v[36:37], v[36:37], 0, v[160:161]
	global_load_dwordx4 v[108:111], v[36:37], off
	v_cmp_le_i32_e32 vcc, s17, v176
	s_and_saveexec_b64 s[10:11], vcc
	s_cbranch_execz .Lmla_skip_b
; template <int TYPE>
; DI void attn_item(KargPtr p, int b, int h, int qb, unsigned char* smem) {
;     ...
;     auto compute = [&](const int kt, const int buf) __attribute__((always_inline)) {
;         const unsigned char* kb = smem + buf * BUFB; const unsigned char* vb = kb + KBYTES;
;         const int k0 = kt * 64;
;         bool need;
;         if (TYPE == 0) {
;             if (!wdone && k0 <= qw + 31) wdone = (__all(qbound + *(const float*)(vb + VBYTES) - m < -150.f) != 0);
;             need = (k0 <= qw + 31) && !wdone;
;         }
;         else if (TYPE == 1) need = (k0 <= qw);
;         else need = (k0 <= qw + 30) && !wdone;
;         if (need) {
;             f32x16 s0, s1;
; #pragma unroll
;             for (int i = 0; i < 16; ++i) { s0[i] = 0.f; s1[i] = 0.f; }
; #pragma unroll
;             for (int ks = 0; ks < KS; ++ks) {
;                 const bf16x8 a0 = *(const bf16x8*)(kb + r * KROWB + ks * 32 + hh * 16);
;                 const bf16x8 a1 = *(const bf16x8*)(kb + (32 + r) * KROWB + ks * 32 + hh * 16);
;                 s0 = MFMA(a0, qfrag[ks], s0); s1 = MFMA(a1, qfrag[ks], s1);
;             }
;             if (TYPE != 2) {
;                 if (TYPE == 0) {
;                     if (k0 + 63 > qw) {
;                         asm volatile("");
;                         const int rel = myq - k0 - 4 * hh;
; #pragma unroll
;                         for (int i = 0; i < 16; ++i) {
;                             const int off = 8 * (i >> 2) + (i & 3);
;                             if (off > rel) s0[i] = -1e30f;
;                             if (off + 32 > rel) s1[i] = -1e30f;
;                         }
;                     }
;                 }
;                 float mx = s0[0];
; #pragma unroll
;                 for (int i = 1; i < 16; ++i) mx = fmaxf(mx, s0[i]);
; #pragma unroll
;                 for (int i = 0; i < 16; ++i) mx = fmaxf(mx, s1[i]);
;                 mx = fmaxf(mx, __shfl_xor(mx, 32));
;                 const float mnew = fmaxf(m, mx);
;                 const float alpha = fexp2(m - mnew);
;                 m = mnew;
;                 float ps = 0.f;
; #pragma unroll
;                 for (int i = 0; i < 16; i += 2) {
;                     const f32x2_t mm = {mnew, mnew};
;                     const f32x2_t d0 = (f32x2_t){s0[i], s0[i + 1]} - mm, d1 = (f32x2_t){s1[i], s1[i + 1]} - mm;
	ds_read_b128 v[52:55], v183 offset:29440
	ds_read_b128 v[36:39], v183 offset:22784
	ds_read_b128 v[56:59], v183 offset:22816
	ds_read_b128 v[138:141], v183 offset:29472
	s_waitcnt lgkmcnt(2)
	v_mfma_f32_32x32x16_bf16 v[36:51], v[36:39], v[68:71], 0
	s_waitcnt lgkmcnt(1)
	v_mfma_f32_32x32x16_bf16 v[36:51], v[56:59], v[72:75], v[36:51]
	ds_read_b128 v[56:59], v183 offset:22848
	ds_read_b128 v[142:145], v183 offset:29504
	s_waitcnt lgkmcnt(1)
	v_mfma_f32_32x32x16_bf16 v[36:51], v[56:59], v[76:79], v[36:51]
	ds_read_b128 v[56:59], v183 offset:22880
	ds_read_b128 v[150:153], v183 offset:29536
	s_waitcnt lgkmcnt(1)
	v_mfma_f32_32x32x16_bf16 v[36:51], v[56:59], v[80:83], v[36:51]
	ds_read_b128 v[56:59], v183 offset:22912
	ds_read_b128 v[164:167], v183 offset:29568
	s_waitcnt lgkmcnt(1)
	v_mfma_f32_32x32x16_bf16 v[36:51], v[56:59], v[84:87], v[36:51]
	ds_read_b128 v[56:59], v183 offset:22944
	ds_read_b128 v[168:171], v183 offset:29600
	s_waitcnt lgkmcnt(1)
	v_mfma_f32_32x32x16_bf16 v[36:51], v[56:59], v[88:91], v[36:51]
	s_nop 11
	v_max_f32_e32 v2, v37, v37
	v_max_f32_e32 v56, v36, v36
	v_max_f32_e32 v2, v56, v2
	v_mfma_f32_32x32x16_bf16 v[52:67], v[52:55], v[68:71], 0
	v_max3_f32 v2, v2, v38, v39
	v_max3_f32 v2, v2, v40, v41
	v_max3_f32 v2, v2, v42, v43
	v_max3_f32 v2, v2, v44, v45
	v_max3_f32 v2, v2, v46, v47
	v_max3_f32 v2, v2, v48, v49
	v_max3_f32 v2, v2, v50, v51
	v_mfma_f32_32x32x16_bf16 v[52:67], v[138:141], v[72:75], v[52:67]
	v_and_b32_e32 v139, 64, v205
	v_xor_b32_e32 v138, 32, v205
	v_add_u32_e32 v139, 64, v139
	v_cmp_lt_i32_e32 vcc, v138, v139
	s_nop 1
	v_cndmask_b32_e32 v138, v205, v138, vcc
	v_mfma_f32_32x32x16_bf16 v[52:67], v[142:145], v[76:79], v[52:67]
	v_lshlrev_b32_e32 v138, 2, v138
	v_mfma_f32_32x32x16_bf16 v[52:67], v[150:153], v[80:83], v[52:67]
	v_mfma_f32_32x32x16_bf16 v[52:67], v[164:167], v[84:87], v[52:67]
	s_waitcnt lgkmcnt(0)
	v_mfma_f32_32x32x16_bf16 v[52:67], v[168:171], v[88:91], v[52:67]
	s_nop 11
	v_max3_f32 v2, v2, v52, v53
	v_max3_f32 v2, v2, v54, v55
	v_max3_f32 v2, v2, v56, v57
	v_max3_f32 v2, v2, v58, v59
	v_max3_f32 v2, v2, v60, v61
	v_max3_f32 v2, v2, v62, v63
	v_max3_f32 v2, v2, v64, v65
	v_max3_f32 v2, v2, v66, v67
	v_mov_b32_e32 v138, v2
	v_mov_b32_e32 v225, v2
	s_nop 1
	v_permlane32_swap_b32_e32 v138, v225
	v_max3_f32 v2, v163, v138, v225
	v_pk_add_f32 v[36:37], v[36:37], v[2:3] op_sel_hi:[1,0] neg_lo:[0,1] neg_hi:[0,1]
	v_sub_f32_e32 v138, v163, v2
	v_pk_add_f32 v[52:53], v[52:53], v[2:3] op_sel_hi:[1,0] neg_lo:[0,1] neg_hi:[0,1]
	v_exp_f32_e32 v163, v36
	v_exp_f32_e32 v167, v37
	v_pk_add_f32 v[36:37], v[38:39], v[2:3] op_sel_hi:[1,0] neg_lo:[0,1] neg_hi:[0,1]
	v_pk_add_f32 v[38:39], v[54:55], v[2:3] op_sel_hi:[1,0] neg_lo:[0,1] neg_hi:[0,1]
	v_exp_f32_e32 v165, v52
	v_exp_f32_e32 v169, v53
	v_exp_f32_e32 v162, v36
	v_exp_f32_e32 v166, v37
	v_exp_f32_e32 v164, v38
	v_exp_f32_e32 v168, v39
	v_pk_add_f32 v[44:45], v[44:45], v[2:3] op_sel_hi:[1,0] neg_lo:[0,1] neg_hi:[0,1]
	v_pk_add_f32 v[36:37], v[166:167], v[162:163]
	v_pk_add_f32 v[52:53], v[60:61], v[2:3] op_sel_hi:[1,0] neg_lo:[0,1] neg_hi:[0,1]
	v_pk_add_f32 v[38:39], v[168:169], v[164:165]
	v_pk_add_f32 v[54:55], v[62:63], v[2:3] op_sel_hi:[1,0] neg_lo:[0,1] neg_hi:[0,1]
	v_pk_add_f32 v[36:37], v[38:39], v[36:37]
	v_pk_add_f32 v[38:39], v[40:41], v[2:3] op_sel_hi:[1,0] neg_lo:[0,1] neg_hi:[0,1]
	v_pk_add_f32 v[40:41], v[56:57], v[2:3] op_sel_hi:[1,0] neg_lo:[0,1] neg_hi:[0,1]
	v_exp_f32_e32 v171, v38
	v_exp_f32_e32 v173, v39
	v_exp_f32_e32 v170, v40
	v_exp_f32_e32 v172, v41
	v_pk_add_f32 v[40:41], v[42:43], v[2:3] op_sel_hi:[1,0] neg_lo:[0,1] neg_hi:[0,1]
	v_pk_add_f32 v[42:43], v[58:59], v[2:3] op_sel_hi:[1,0] neg_lo:[0,1] neg_hi:[0,1]
	v_add_f32_e32 v37, 0, v37
	v_pk_add_f32 v[38:39], v[172:173], v[170:171]
	v_exp_f32_e32 v139, v40
	v_pk_add_f32 v[38:39], v[38:39], v[38:39] op_sel_hi:[0,1]
	v_exp_f32_e32 v140, v41
	v_exp_f32_e32 v141, v42
	v_exp_f32_e32 v142, v43
	s_barrier
; #define MFMA(a, b, c) __builtin_amdgcn_mfma_f32_32x32x16_bf16((a), (b), (c), 0, 0, 0)
; DI unsigned pack_bf16(float lo, float hi) { const f32x2_t v = {lo, hi}; const bf16x2_t b = __builtin_convertvector(v, bf16x2_t); return __builtin_bit_cast(unsigned, b); }
; DI float fexp2(float x) { return __builtin_amdgcn_exp2f(x); }
; template <int TYPE>
; DI void attn_item(KargPtr p, int b, int h, int qb, unsigned char* smem) {
;     ...
;                 for (int i = 0; i < 16; i += 2) {
;                     const f32x2_t mm = {mnew, mnew};
;                     const f32x2_t d0 = (f32x2_t){s0[i], s0[i + 1]} - mm, d1 = (f32x2_t){s1[i], s1[i + 1]} - mm;
;                     s0[i] = fexp2(d0[0]); s0[i + 1] = fexp2(d0[1]); s1[i] = fexp2(d1[0]); s1[i + 1] = fexp2(d1[1]);
;                     ps += (s0[i] + s0[i + 1]) + (s1[i] + s1[i + 1]);
;                 }
;                 lsum = lsum * alpha + ps;
; #pragma unroll
;                 for (int i = 0; i < 16; ++i) { o0[i] *= alpha; o1[i] *= alpha; }
;     ...
; #pragma unroll
;             for (int s2 = 0; s2 < 2; ++s2) {
;                 unsigned pk0[4], pk1[4];
; #pragma unroll
;                 for (int j = 0; j < 4; ++j) { pk0[j] = pack_bf16(s0[8 * s2 + 2 * j], s0[8 * s2 + 2 * j + 1]); pk1[j] = pack_bf16(s1[8 * s2 + 2 * j], s1[8 * s2 + 2 * j + 1]); }
;                 const uint4 u0 = make_uint4(pk0[0], pk0[1], pk0[2], pk0[3]), u1 = make_uint4(pk1[0], pk1[1], pk1[2], pk1[3]);
;                 const bf16x8 pf0 = __builtin_bit_cast(bf16x8, u0), pf1 = __builtin_bit_cast(bf16x8, u1);
;                 const bf16x8 v00 = *(const bf16x8*)(vb + r * VROWB + (16 * s2 + 8 * hh) * 2);
;                 const bf16x8 v01 = *(const bf16x8*)(vb + (32 + r) * VROWB + (16 * s2 + 8 * hh) * 2);
;                 const bf16x8 v10 = *(const bf16x8*)(vb + r * VROWB + (32 + 16 * s2 + 8 * hh) * 2);
;                 const bf16x8 v11 = *(const bf16x8*)(vb + (32 + r) * VROWB + (32 + 16 * s2 + 8 * hh) * 2);
;                 o0 = MFMA(v00, pf0, o0); o1 = MFMA(v01, pf0, o1);
;                 o0 = MFMA(v10, pf1, o0); o1 = MFMA(v11, pf1, o1);
;             }
	v_add_f32_e32 v37, v36, v37
	v_exp_f32_e32 v36, v44
	v_exp_f32_e32 v38, v45
	v_exp_f32_e32 v40, v52
	v_exp_f32_e32 v42, v53
	v_add_f32_e32 v41, v140, v139
	v_add_f32_e32 v43, v142, v141
	v_pk_add_f32 v[44:45], v[38:39], v[36:37]
	v_pk_add_f32 v[52:53], v[42:43], v[40:41]
	v_pk_add_f32 v[48:49], v[48:49], v[2:3] op_sel_hi:[1,0] neg_lo:[0,1] neg_hi:[0,1]
	v_pk_add_f32 v[44:45], v[52:53], v[44:45]
	v_pk_add_f32 v[52:53], v[46:47], v[2:3] op_sel_hi:[1,0] neg_lo:[0,1] neg_hi:[0,1]
	v_exp_f32_e32 v46, v54
	v_exp_f32_e32 v47, v52
	v_exp_f32_e32 v53, v53
	v_exp_f32_e32 v52, v55
	v_pk_add_f32 v[56:57], v[64:65], v[2:3] op_sel_hi:[1,0] neg_lo:[0,1] neg_hi:[0,1]
	v_pk_add_f32 v[44:45], v[44:45], v[44:45] op_sel_hi:[0,1]
	v_exp_f32_e32 v41, v48
	v_pk_add_f32 v[54:55], v[52:53], v[46:47]
	v_exp_f32_e32 v43, v49
	v_pk_add_f32 v[54:55], v[54:55], v[54:55] op_sel_hi:[0,1]
	v_exp_f32_e32 v146, v56
	v_exp_f32_e32 v147, v57
	v_pk_add_f32 v[50:51], v[50:51], v[2:3] op_sel_hi:[1,0] neg_lo:[0,1] neg_hi:[0,1]
	v_pk_add_f32 v[58:59], v[66:67], v[2:3] op_sel_hi:[1,0] neg_lo:[0,1] neg_hi:[0,1]
	v_exp_f32_e32 v44, v50
	v_exp_f32_e32 v54, v51
	v_exp_f32_e32 v48, v58
	v_exp_f32_e32 v56, v59
	v_add_f32_e32 v49, v43, v41
	v_add_f32_e32 v57, v147, v146
	v_pk_add_f32 v[50:51], v[54:55], v[44:45]
	v_pk_add_f32 v[58:59], v[56:57], v[48:49]
	v_cvt_pk_bf16_f32 v62, v165, v169
	v_pk_add_f32 v[50:51], v[58:59], v[50:51]
	v_cvt_pk_bf16_f32 v58, v163, v167
	v_add_f32_e32 v37, v50, v51
	v_exp_f32_e32 v50, v138
	v_cvt_pk_bf16_f32 v59, v162, v166
	v_cvt_pk_bf16_f32 v63, v164, v168
	v_cvt_pk_bf16_f32 v61, v139, v140
	v_cvt_pk_bf16_f32 v65, v141, v142
	ds_read_b128 v[138:141], v184 offset:40704
	ds_read_b128 v[142:145], v184 offset:36160
	ds_read_b128 v[150:153], v184 offset:40768
	ds_read_b128 v[162:165], v184 offset:36096
	ds_read_b128 v[166:169], v184 offset:36128
	v_pk_mul_f32 v[34:35], v[34:35], v[50:51] op_sel_hi:[1,0]
	v_pk_mul_f32 v[32:33], v[32:33], v[50:51] op_sel_hi:[1,0]
	v_pk_mul_f32 v[30:31], v[30:31], v[50:51] op_sel_hi:[1,0]
	v_pk_mul_f32 v[28:29], v[28:29], v[50:51] op_sel_hi:[1,0]
	v_pk_mul_f32 v[26:27], v[26:27], v[50:51] op_sel_hi:[1,0]
	v_pk_mul_f32 v[24:25], v[24:25], v[50:51] op_sel_hi:[1,0]
	v_pk_mul_f32 v[22:23], v[22:23], v[50:51] op_sel_hi:[1,0]
	v_pk_mul_f32 v[20:21], v[20:21], v[50:51] op_sel_hi:[1,0]
	v_pk_mul_f32 v[18:19], v[18:19], v[50:51] op_sel_hi:[1,0]
	v_pk_mul_f32 v[16:17], v[16:17], v[50:51] op_sel_hi:[1,0]
	v_pk_mul_f32 v[14:15], v[14:15], v[50:51] op_sel_hi:[1,0]
	v_pk_mul_f32 v[12:13], v[12:13], v[50:51] op_sel_hi:[1,0]
	v_pk_mul_f32 v[10:11], v[10:11], v[50:51] op_sel_hi:[1,0]
	v_pk_mul_f32 v[8:9], v[8:9], v[50:51] op_sel_hi:[1,0]
	v_pk_mul_f32 v[6:7], v[6:7], v[50:51] op_sel_hi:[1,0]
	v_pk_mul_f32 v[4:5], v[4:5], v[50:51] op_sel_hi:[1,0]
	v_cvt_pk_bf16_f32 v60, v171, v173
	v_cvt_pk_bf16_f32 v64, v170, v172
	v_fmac_f32_e32 v37, v185, v50
	s_waitcnt lgkmcnt(1)
	v_mfma_f32_32x32x16_bf16 v[20:35], v[162:165], v[58:61], v[20:35]
	v_cvt_pk_bf16_f32 v50, v40, v42
	v_cvt_pk_bf16_f32 v39, v47, v53
	v_cvt_pk_bf16_f32 v51, v46, v52
	v_cvt_pk_bf16_f32 v40, v41, v43
	v_cvt_pk_bf16_f32 v41, v44, v54
	v_cvt_pk_bf16_f32 v53, v48, v56
	ds_read_b128 v[42:45], v184 offset:40736
	ds_read_b128 v[46:49], v184 offset:36192
	ds_read_b128 v[54:57], v184 offset:40800
	v_mfma_f32_32x32x16_bf16 v[4:19], v[138:141], v[58:61], v[4:19]
	v_cvt_pk_bf16_f32 v38, v36, v38
	v_cvt_pk_bf16_f32 v52, v146, v147
	v_mov_b32_e32 v185, v37
	v_mov_b32_e32 v163, v2
	v_mfma_f32_32x32x16_bf16 v[20:35], v[142:145], v[62:65], v[20:35]
	v_mfma_f32_32x32x16_bf16 v[4:19], v[150:153], v[62:65], v[4:19]
	s_waitcnt lgkmcnt(3)
	v_mfma_f32_32x32x16_bf16 v[20:35], v[166:169], v[38:41], v[20:35]
	s_waitcnt lgkmcnt(2)
	v_mfma_f32_32x32x16_bf16 v[4:19], v[42:45], v[38:41], v[4:19]
	s_waitcnt lgkmcnt(1)
	v_mfma_f32_32x32x16_bf16 v[20:35], v[46:49], v[50:53], v[20:35]
	s_waitcnt lgkmcnt(0)
	v_mfma_f32_32x32x16_bf16 v[4:19], v[54:57], v[50:53], v[4:19]
	s_branch .LBB0_590

; #define MFMA(a, b, c) __builtin_amdgcn_mfma_f32_32x32x16_bf16((a), (b), (c), 0, 0, 0)
; template <int TYPE>
; DI void attn_item(KargPtr p, int b, int h, int qb, unsigned char* smem) {
;     ...
;         if (TYPE == 0) {
;             if (!wdone && k0 <= qw + 31) wdone = (__all(qbound + *(const float*)(vb + VBYTES) - m < -150.f) != 0);
;             need = (k0 <= qw + 31) && !wdone;
;         }
;         else if (TYPE == 1) need = (k0 <= qw);
;         else need = (k0 <= qw + 30) && !wdone;
;         if (need) {
;             f32x16 s0, s1;
; #pragma unroll
;             for (int i = 0; i < 16; ++i) { s0[i] = 0.f; s1[i] = 0.f; }
; #pragma unroll
;             for (int ks = 0; ks < KS; ++ks) {
;                 const bf16x8 a0 = *(const bf16x8*)(kb + r * KROWB + ks * 32 + hh * 16);
;                 const bf16x8 a1 = *(const bf16x8*)(kb + (32 + r) * KROWB + ks * 32 + hh * 16);
;                 s0 = MFMA(a0, qfrag[ks], s0); s1 = MFMA(a1, qfrag[ks], s1);
;             }
;             if (TYPE != 2) {
;                 if (TYPE == 0) {
;                     if (k0 + 63 > qw) {
;                         asm volatile("");
;                         const int rel = myq - k0 - 4 * hh;
; #pragma unroll
;                         for (int i = 0; i < 16; ++i) {
;                             const int off = 8 * (i >> 2) + (i & 3);
;                             if (off > rel) s0[i] = -1e30f;
;                             if (off + 32 > rel) s1[i] = -1e30f;
;                         }
;                     }
.LBB0_610:
	s_or_b64 exec, exec, s[14:15]
	s_nor_b64 s[10:11], s[12:13], s[10:11]
	s_and_saveexec_b64 s[90:91], s[10:11]
	s_cbranch_execz .LBB0_614
	v_add_u32_e32 v0, v185, v130
	ds_read_b128 v[48:51], v0 offset:20736
	ds_read_b128 v[138:141], v0 offset:20768
	ds_read_b128 v[64:67], v0 offset:26368
	ds_read_b128 v[226:229], v0 offset:26400
	ds_read_b128 v[230:233], v0 offset:20800
	ds_read_b128 v[234:237], v0 offset:26432
	ds_read_b128 v[238:241], v0 offset:20832
	ds_read_b128 v[242:245], v0 offset:26464
	ds_read_b128 v[246:249], v0 offset:20864
	ds_read_b128 v[250:253], v0 offset:26496
	v_cmp_gt_i32_e32 vcc, s74, v172
	s_waitcnt lgkmcnt(9)
	v_mfma_f32_32x32x16_bf16 v[48:63], v[48:51], v[80:83], 0
	s_waitcnt lgkmcnt(8)
	v_mfma_f32_32x32x16_bf16 v[48:63], v[138:141], v[84:87], v[48:63]
	s_waitcnt lgkmcnt(7)
	v_mfma_f32_32x32x16_bf16 v[64:79], v[64:67], v[80:83], 0
	s_waitcnt lgkmcnt(6)
	v_mfma_f32_32x32x16_bf16 v[64:79], v[226:229], v[84:87], v[64:79]
	s_waitcnt lgkmcnt(5)
	v_mfma_f32_32x32x16_bf16 v[48:63], v[230:233], v[88:91], v[48:63]
	s_waitcnt lgkmcnt(4)
	v_mfma_f32_32x32x16_bf16 v[64:79], v[234:237], v[88:91], v[64:79]
	s_waitcnt lgkmcnt(3)
	v_mfma_f32_32x32x16_bf16 v[48:63], v[238:241], v[92:95], v[48:63]
	s_waitcnt lgkmcnt(2)
	v_mfma_f32_32x32x16_bf16 v[64:79], v[242:245], v[92:95], v[64:79]
	s_waitcnt lgkmcnt(1)
	v_mfma_f32_32x32x16_bf16 v[48:63], v[246:249], v[104:107], v[48:63]
	s_waitcnt lgkmcnt(0)
	v_mfma_f32_32x32x16_bf16 v[64:79], v[250:253], v[104:107], v[64:79]
	s_and_saveexec_b64 s[86:87], vcc
	s_cbranch_execz .LBB0_613
	v_cmp_gt_i32_e64 s[70:71], 26, v188
	v_cmp_gt_i32_e64 s[72:73], 27, v188
	v_cmp_gt_i32_e64 s[68:69], 25, v188
	s_and_b64 s[70:71], s[72:73], s[70:71]
	v_cmp_gt_i32_e64 s[66:67], 24, v188
	s_and_b64 s[68:69], s[70:71], s[68:69]
	v_cmp_gt_i32_e64 s[64:65], 19, v188
	s_and_b64 s[66:67], s[68:69], s[66:67]
	v_cmp_gt_i32_e64 s[62:63], 18, v188
	s_and_b64 s[64:65], s[66:67], s[64:65]
	v_cmp_gt_i32_e64 s[60:61], 17, v188
	s_and_b64 s[62:63], s[64:65], s[62:63]
	v_cmp_gt_i32_e64 s[58:59], 16, v188
	s_and_b64 s[60:61], s[62:63], s[60:61]
	v_cmp_gt_i32_e64 s[56:57], 11, v188
	s_and_b64 s[58:59], s[60:61], s[58:59]
	v_cmp_gt_i32_e64 s[54:55], 10, v188
	s_and_b64 s[56:57], s[58:59], s[56:57]
	v_cmp_gt_i32_e64 s[52:53], 9, v188
	s_and_b64 s[54:55], s[56:57], s[54:55]
	v_cmp_gt_i32_e64 s[50:51], 8, v188
	s_and_b64 s[52:53], s[54:55], s[52:53]
	v_cmp_gt_i32_e64 s[48:49], 3, v188
	s_and_b64 s[50:51], s[52:53], s[50:51]
	v_cmp_gt_i32_e64 s[46:47], 2, v188
	s_and_b64 s[48:49], s[50:51], s[48:49]
	v_cmp_gt_i32_e64 s[44:45], 1, v188
	s_and_b64 s[46:47], s[48:49], s[46:47]
	v_cmp_gt_i32_e64 s[42:43], 0, v188
	s_and_b64 s[44:45], s[46:47], s[44:45]
	s_and_b64 s[42:43], s[44:45], s[42:43]
	v_cmp_gt_i32_e64 s[38:39], 58, v188
	v_cndmask_b32_e64 v48, v48, v207, s[42:43]
	v_cmp_gt_i32_e64 s[42:43], 59, v188
	v_cmp_gt_i32_e64 s[36:37], 57, v188
	s_and_b64 s[38:39], s[42:43], s[38:39]
	v_cmp_gt_i32_e64 s[34:35], 56, v188
	s_and_b64 s[36:37], s[38:39], s[36:37]
	v_cmp_gt_i32_e64 s[30:31], 51, v188
	s_and_b64 s[34:35], s[36:37], s[34:35]
	v_cmp_gt_i32_e64 s[28:29], 50, v188
	s_and_b64 s[30:31], s[34:35], s[30:31]
	v_cmp_gt_i32_e64 s[26:27], 49, v188
	s_and_b64 s[28:29], s[30:31], s[28:29]
	v_cmp_gt_i32_e64 s[24:25], 48, v188
	s_and_b64 s[26:27], s[28:29], s[26:27]
	v_cmp_gt_i32_e64 s[22:23], 43, v188
	s_and_b64 s[24:25], s[26:27], s[24:25]
	v_cmp_gt_i32_e64 s[20:21], 42, v188
	s_and_b64 s[22:23], s[24:25], s[22:23]
	v_cmp_gt_i32_e64 s[18:19], 41, v188
	s_and_b64 s[20:21], s[22:23], s[20:21]
	v_cmp_gt_i32_e64 s[16:17], 40, v188
	s_and_b64 s[18:19], s[20:21], s[18:19]
	v_cmp_gt_i32_e64 s[14:15], 35, v188
	s_and_b64 s[16:17], s[18:19], s[16:17]
	v_cmp_gt_i32_e64 s[12:13], 34, v188
	s_and_b64 s[14:15], s[16:17], s[14:15]
	v_cmp_gt_i32_e64 s[10:11], 33, v188
	s_and_b64 s[12:13], s[14:15], s[12:13]
	v_cmp_gt_i32_e32 vcc, 32, v188
	v_cndmask_b32_e64 v61, v61, v207, s[68:69]
	v_readlane_b32 s68, v254, 63
	s_and_b64 s[10:11], s[12:13], s[10:11]
	v_readlane_b32 s69, v255, 0
	v_cndmask_b32_e64 v79, v79, v207, s[42:43]
	v_readlane_b32 s42, v255, 17
	s_and_b64 vcc, s[10:11], vcc
	v_cndmask_b32_e64 v63, v63, v207, s[72:73]
	v_cndmask_b32_e64 v62, v62, v207, s[70:71]
	s_mov_b32 s71, 0x800000
	s_mov_b32 s70, 0x24000
	s_mov_b32 s69, 0x8000
	v_cndmask_b32_e64 v60, v60, v207, s[66:67]
	s_mov_b32 s67, 0x18000
	s_movk_i32 s66, 0x6000
	v_cndmask_b32_e64 v59, v59, v207, s[64:65]
	s_mov_b32 s65, 0x10000
	v_readlane_b32 s64, v255, 2
	v_cndmask_b32_e64 v58, v58, v207, s[62:63]
	s_movk_i32 s62, 0x1fff
	v_readlane_b32 s63, v255, 1
	v_cndmask_b32_e64 v57, v57, v207, s[60:61]
	v_readlane_b32 s61, v255, 19
	s_mov_b32 s60, 0xc32a0000
	v_cndmask_b32_e64 v56, v56, v207, s[58:59]
	v_cndmask_b32_e64 v55, v55, v207, s[56:57]
	v_cndmask_b32_e64 v54, v54, v207, s[54:55]
	v_cndmask_b32_e64 v53, v53, v207, s[52:53]
	v_cndmask_b32_e64 v52, v52, v207, s[50:51]
	v_cndmask_b32_e64 v51, v51, v207, s[48:49]
	v_cndmask_b32_e64 v50, v50, v207, s[46:47]
	v_cndmask_b32_e64 v49, v49, v207, s[44:45]
	v_readlane_b32 s43, v255, 18
	v_cndmask_b32_e64 v78, v78, v207, s[38:39]
	s_mov_b64 s[38:39], 0x1000
	v_cndmask_b32_e64 v77, v77, v207, s[36:37]
	s_mov_b32 s36, 0x358637bd
	v_cndmask_b32_e64 v76, v76, v207, s[34:35]
	v_cndmask_b32_e64 v75, v75, v207, s[30:31]
	s_mov_b32 s30, 0x3a800000
	v_cndmask_b32_e64 v74, v74, v207, s[28:29]
	v_cndmask_b32_e64 v73, v73, v207, s[26:27]
	v_readlane_b32 s26, v255, 21
	v_cndmask_b32_e64 v72, v72, v207, s[24:25]
	v_cndmask_b32_e64 v71, v71, v207, s[22:23]
	v_cndmask_b32_e64 v70, v70, v207, s[20:21]
	v_cndmask_b32_e64 v69, v69, v207, s[18:19]
	v_cndmask_b32_e64 v68, v68, v207, s[16:17]
	v_cndmask_b32_e64 v67, v67, v207, s[14:15]
	v_cndmask_b32_e64 v66, v66, v207, s[12:13]
	v_cndmask_b32_e64 v65, v65, v207, s[10:11]
	v_cndmask_b32_e32 v64, v64, v207, vcc
; #define MFMA(a, b, c) __builtin_amdgcn_mfma_f32_32x32x16_bf16((a), (b), (c), 0, 0, 0)
; DI float fexp2(float x) { return __builtin_amdgcn_exp2f(x); }
; template <int TYPE>
; DI void attn_item(KargPtr p, int b, int h, int qb, unsigned char* smem) {
;     ...
;                 float mx = s0[0];
; #pragma unroll
;                 for (int i = 1; i < 16; ++i) mx = fmaxf(mx, s0[i]);
; #pragma unroll
;                 for (int i = 0; i < 16; ++i) mx = fmaxf(mx, s1[i]);
;                 mx = fmaxf(mx, __shfl_xor(mx, 32));
;                 const float mnew = fmaxf(m, mx);
;                 const float alpha = fexp2(m - mnew);
;                 m = mnew;
;                 float ps = 0.f;
; #pragma unroll
;                 for (int i = 0; i < 16; i += 2) {
;                     const f32x2_t mm = {mnew, mnew};
;                     const f32x2_t d0 = (f32x2_t){s0[i], s0[i + 1]} - mm, d1 = (f32x2_t){s1[i], s1[i + 1]} - mm;
;                     s0[i] = fexp2(d0[0]); s0[i + 1] = fexp2(d0[1]); s1[i] = fexp2(d1[0]); s1[i + 1] = fexp2(d1[1]);
;                     ps += (s0[i] + s0[i + 1]) + (s1[i] + s1[i + 1]);
;                 }
;                 lsum = lsum * alpha + ps;
; #pragma unroll
;                 for (int i = 0; i < 16; ++i) { o0[i] *= alpha; o1[i] *= alpha; }
;     ...
; #pragma unroll
;             for (int s2 = 0; s2 < 2; ++s2) {
;                 unsigned pk0[4], pk1[4];
; #pragma unroll
;                 for (int j = 0; j < 4; ++j) { pk0[j] = pack_bf16(s0[8 * s2 + 2 * j], s0[8 * s2 + 2 * j + 1]); pk1[j] = pack_bf16(s1[8 * s2 + 2 * j], s1[8 * s2 + 2 * j + 1]); }
;                 const uint4 u0 = make_uint4(pk0[0], pk0[1], pk0[2], pk0[3]), u1 = make_uint4(pk1[0], pk1[1], pk1[2], pk1[3]);
;                 const bf16x8 pf0 = __builtin_bit_cast(bf16x8, u0), pf1 = __builtin_bit_cast(bf16x8, u1);
;                 const bf16x8 v00 = *(const bf16x8*)(vb + r * VROWB + (16 * s2 + 8 * hh) * 2);
;                 const bf16x8 v01 = *(const bf16x8*)(vb + (32 + r) * VROWB + (16 * s2 + 8 * hh) * 2);
;                 const bf16x8 v10 = *(const bf16x8*)(vb + r * VROWB + (32 + 16 * s2 + 8 * hh) * 2);
;                 const bf16x8 v11 = *(const bf16x8*)(vb + (32 + r) * VROWB + (32 + 16 * s2 + 8 * hh) * 2);
;                 o0 = MFMA(v00, pf0, o0); o1 = MFMA(v01, pf0, o1);
;                 o0 = MFMA(v10, pf1, o0); o1 = MFMA(v11, pf1, o1);
;             }
.LBB0_613:
	s_or_b64 exec, exec, s[86:87]
	s_nop 5
	v_max_f32_e32 v0, v49, v49
	v_max_f32_e32 v1, v48, v48
	v_max_f32_e32 v0, v1, v0
	v_max3_f32 v0, v0, v50, v51
	v_max3_f32 v0, v0, v52, v53
	v_max3_f32 v0, v0, v54, v55
	v_max3_f32 v0, v0, v56, v57
	v_max3_f32 v0, v0, v58, v59
	v_max3_f32 v0, v0, v60, v61
	v_max3_f32 v0, v0, v62, v63
	v_max3_f32 v0, v0, v64, v65
	v_max3_f32 v0, v0, v66, v67
	v_max3_f32 v0, v0, v68, v69
	v_max3_f32 v0, v0, v70, v71
	v_max3_f32 v0, v0, v72, v73
	v_max3_f32 v0, v0, v74, v75
	v_max3_f32 v0, v0, v76, v77
	v_max3_f32 v0, v0, v78, v79
	v_mov_b32_e32 v1, v0
	v_mov_b32_e32 v225, v0
	s_nop 1
	v_permlane32_swap_b32_e32 v1, v225
	v_max3_f32 v0, v160, v1, v225
	v_pk_add_f32 v[48:49], v[48:49], v[0:1] op_sel_hi:[1,0] neg_lo:[0,1] neg_hi:[0,1]
	v_pk_add_f32 v[64:65], v[64:65], v[0:1] op_sel_hi:[1,0] neg_lo:[0,1] neg_hi:[0,1]
	v_exp_f32_e32 v161, v48
	v_exp_f32_e32 v165, v49
	v_pk_add_f32 v[48:49], v[50:51], v[0:1] op_sel_hi:[1,0] neg_lo:[0,1] neg_hi:[0,1]
	v_pk_add_f32 v[50:51], v[66:67], v[0:1] op_sel_hi:[1,0] neg_lo:[0,1] neg_hi:[0,1]
	v_sub_f32_e32 v2, v160, v0
	v_exp_f32_e32 v163, v64
	v_exp_f32_e32 v167, v65
	v_exp_f32_e32 v160, v48
	v_exp_f32_e32 v164, v49
	v_exp_f32_e32 v162, v50
	v_exp_f32_e32 v166, v51
	v_exp_f32_e32 v2, v2
	v_pk_add_f32 v[48:49], v[164:165], v[160:161]
	v_pk_add_f32 v[50:51], v[166:167], v[162:163]
	s_nop 0
	v_pk_add_f32 v[48:49], v[50:51], v[48:49]
	v_pk_mul_f32 v[46:47], v[46:47], v[2:3] op_sel_hi:[1,0]
	v_add_f32_e32 v1, 0, v49
	v_pk_add_f32 v[50:51], v[52:53], v[0:1] op_sel_hi:[1,0] neg_lo:[0,1] neg_hi:[0,1]
	v_pk_add_f32 v[52:53], v[68:69], v[0:1] op_sel_hi:[1,0] neg_lo:[0,1] neg_hi:[0,1]
	v_exp_f32_e32 v169, v50
	v_exp_f32_e32 v171, v51
	v_exp_f32_e32 v168, v52
	v_exp_f32_e32 v170, v53
	v_pk_add_f32 v[52:53], v[54:55], v[0:1] op_sel_hi:[1,0] neg_lo:[0,1] neg_hi:[0,1]
	v_pk_add_f32 v[54:55], v[70:71], v[0:1] op_sel_hi:[1,0] neg_lo:[0,1] neg_hi:[0,1]
	v_exp_f32_e32 v138, v52
	v_pk_add_f32 v[50:51], v[170:171], v[168:169]
	v_exp_f32_e32 v139, v53
	v_pk_add_f32 v[50:51], v[50:51], v[50:51] op_sel_hi:[0,1]
	v_exp_f32_e32 v140, v54
	v_exp_f32_e32 v141, v55
	v_pk_add_f32 v[56:57], v[56:57], v[0:1] op_sel_hi:[1,0] neg_lo:[0,1] neg_hi:[0,1]
	v_pk_add_f32 v[64:65], v[72:73], v[0:1] op_sel_hi:[1,0] neg_lo:[0,1] neg_hi:[0,1]
	v_add_f32_e32 v49, v48, v1
	v_exp_f32_e32 v48, v56
	v_exp_f32_e32 v50, v57
	v_exp_f32_e32 v52, v64
	v_exp_f32_e32 v54, v65
	v_add_f32_e32 v53, v139, v138
	v_add_f32_e32 v55, v141, v140
	v_pk_add_f32 v[56:57], v[50:51], v[48:49]
	v_pk_add_f32 v[64:65], v[54:55], v[52:53]
	v_pk_add_f32 v[66:67], v[74:75], v[0:1] op_sel_hi:[1,0] neg_lo:[0,1] neg_hi:[0,1]
	v_pk_add_f32 v[56:57], v[64:65], v[56:57]
	v_pk_add_f32 v[64:65], v[58:59], v[0:1] op_sel_hi:[1,0] neg_lo:[0,1] neg_hi:[0,1]
	v_exp_f32_e32 v58, v66
	v_exp_f32_e32 v59, v64
	v_exp_f32_e32 v65, v65
	v_exp_f32_e32 v64, v67
	v_pk_add_f32 v[60:61], v[60:61], v[0:1] op_sel_hi:[1,0] neg_lo:[0,1] neg_hi:[0,1]
	v_pk_add_f32 v[68:69], v[76:77], v[0:1] op_sel_hi:[1,0] neg_lo:[0,1] neg_hi:[0,1]
	v_pk_add_f32 v[56:57], v[56:57], v[56:57] op_sel_hi:[0,1]
	v_pk_add_f32 v[66:67], v[64:65], v[58:59]
	v_exp_f32_e32 v51, v60
	v_pk_add_f32 v[66:67], v[66:67], v[66:67] op_sel_hi:[0,1]
	v_exp_f32_e32 v55, v61
	v_exp_f32_e32 v146, v68
	v_exp_f32_e32 v147, v69
	v_pk_add_f32 v[62:63], v[62:63], v[0:1] op_sel_hi:[1,0] neg_lo:[0,1] neg_hi:[0,1]
	v_pk_add_f32 v[70:71], v[78:79], v[0:1] op_sel_hi:[1,0] neg_lo:[0,1] neg_hi:[0,1]
	v_exp_f32_e32 v56, v62
	v_exp_f32_e32 v66, v63
	v_exp_f32_e32 v60, v70
	v_exp_f32_e32 v68, v71
	v_add_f32_e32 v61, v55, v51
	v_add_f32_e32 v69, v147, v146
	v_pk_add_f32 v[62:63], v[66:67], v[56:57]
	v_pk_add_f32 v[70:71], v[68:69], v[60:61]
	v_pk_mul_f32 v[44:45], v[44:45], v[2:3] op_sel_hi:[1,0]
	v_pk_add_f32 v[62:63], v[70:71], v[62:63]
	v_pk_mul_f32 v[42:43], v[42:43], v[2:3] op_sel_hi:[1,0]
	v_add_f32_e32 v1, v62, v63
	v_fmac_f32_e32 v1, v191, v2
	v_pk_mul_f32 v[40:41], v[40:41], v[2:3] op_sel_hi:[1,0]
	v_pk_mul_f32 v[38:39], v[38:39], v[2:3] op_sel_hi:[1,0]
	v_pk_mul_f32 v[36:37], v[36:37], v[2:3] op_sel_hi:[1,0]
	v_pk_mul_f32 v[34:35], v[34:35], v[2:3] op_sel_hi:[1,0]
	v_pk_mul_f32 v[32:33], v[32:33], v[2:3] op_sel_hi:[1,0]
	v_pk_mul_f32 v[30:31], v[30:31], v[2:3] op_sel_hi:[1,0]
	v_pk_mul_f32 v[28:29], v[28:29], v[2:3] op_sel_hi:[1,0]
	v_pk_mul_f32 v[26:27], v[26:27], v[2:3] op_sel_hi:[1,0]
	v_pk_mul_f32 v[24:25], v[24:25], v[2:3] op_sel_hi:[1,0]
	v_pk_mul_f32 v[22:23], v[22:23], v[2:3] op_sel_hi:[1,0]
	v_pk_mul_f32 v[20:21], v[20:21], v[2:3] op_sel_hi:[1,0]
	v_pk_mul_f32 v[18:19], v[18:19], v[2:3] op_sel_hi:[1,0]
	v_pk_mul_f32 v[16:17], v[16:17], v[2:3] op_sel_hi:[1,0]
	v_add_u32_e32 v2, v186, v130
	v_cvt_pk_bf16_f32 v70, v161, v165
	v_cvt_pk_bf16_f32 v74, v163, v167
	v_cvt_pk_bf16_f32 v71, v160, v164
	v_cvt_pk_bf16_f32 v75, v162, v166
	v_cvt_pk_bf16_f32 v73, v138, v139
	v_cvt_pk_bf16_f32 v77, v140, v141
	ds_read_b128 v[138:141], v2 offset:36608
	ds_read_b128 v[142:145], v2 offset:32064
	ds_read_b128 v[150:153], v2 offset:36672
	ds_read_b128 v[160:163], v2 offset:32000
	ds_read_b128 v[164:167], v2 offset:32032
	v_cvt_pk_bf16_f32 v72, v169, v171
	v_cvt_pk_bf16_f32 v76, v168, v170
	v_cvt_pk_bf16_f32 v48, v48, v50
	s_waitcnt lgkmcnt(1)
	v_mfma_f32_32x32x16_bf16 v[32:47], v[160:163], v[70:73], v[32:47]
	v_cvt_pk_bf16_f32 v49, v59, v65
	v_cvt_pk_bf16_f32 v53, v58, v64
	v_cvt_pk_bf16_f32 v50, v51, v55
	v_cvt_pk_bf16_f32 v51, v56, v66
	v_cvt_pk_bf16_f32 v55, v60, v68
	ds_read_b128 v[56:59], v2 offset:36640
	ds_read_b128 v[60:63], v2 offset:32096
	ds_read_b128 v[64:67], v2 offset:36704
	v_cvt_pk_bf16_f32 v52, v52, v54
	v_mfma_f32_32x32x16_bf16 v[16:31], v[138:141], v[70:73], v[16:31]
	v_cvt_pk_bf16_f32 v54, v146, v147
	v_mov_b32_e32 v191, v1
	v_mov_b32_e32 v160, v0
	v_mfma_f32_32x32x16_bf16 v[32:47], v[142:145], v[74:77], v[32:47]
	v_mfma_f32_32x32x16_bf16 v[16:31], v[150:153], v[74:77], v[16:31]
	s_waitcnt lgkmcnt(3)
	v_mfma_f32_32x32x16_bf16 v[32:47], v[164:167], v[48:51], v[32:47]
	s_waitcnt lgkmcnt(2)
	v_mfma_f32_32x32x16_bf16 v[16:31], v[56:59], v[48:51], v[16:31]
	s_waitcnt lgkmcnt(1)
	v_mfma_f32_32x32x16_bf16 v[32:47], v[60:63], v[52:55], v[32:47]
	s_waitcnt lgkmcnt(0)
	v_mfma_f32_32x32x16_bf16 v[16:31], v[64:67], v[52:55], v[16:31]

; #define MFMA(a, b, c) __builtin_amdgcn_mfma_f32_32x32x16_bf16((a), (b), (c), 0, 0, 0)
; template <int TYPE>
; DI void attn_item(KargPtr p, int b, int h, int qb, unsigned char* smem) {
;     ...
;         if (TYPE == 0) {
;             if (!wdone && k0 <= qw + 31) wdone = (__all(qbound + *(const float*)(vb + VBYTES) - m < -150.f) != 0);
;             need = (k0 <= qw + 31) && !wdone;
;         }
;         else if (TYPE == 1) need = (k0 <= qw);
;         else need = (k0 <= qw + 30) && !wdone;
;         if (need) {
;             f32x16 s0, s1;
; #pragma unroll
;             for (int i = 0; i < 16; ++i) { s0[i] = 0.f; s1[i] = 0.f; }
; #pragma unroll
;             for (int ks = 0; ks < KS; ++ks) {
;                 const bf16x8 a0 = *(const bf16x8*)(kb + r * KROWB + ks * 32 + hh * 16);
;                 const bf16x8 a1 = *(const bf16x8*)(kb + (32 + r) * KROWB + ks * 32 + hh * 16);
;                 s0 = MFMA(a0, qfrag[ks], s0); s1 = MFMA(a1, qfrag[ks], s1);
;             }
;             if (TYPE != 2) {
;                 if (TYPE == 0) {
;                     if (k0 + 63 > qw) {
;                         asm volatile("");
;                         const int rel = myq - k0 - 4 * hh;
; #pragma unroll
;                         for (int i = 0; i < 16; ++i) {
;                             const int off = 8 * (i >> 2) + (i & 3);
;                             if (off > rel) s0[i] = -1e30f;
;                             if (off + 32 > rel) s1[i] = -1e30f;
;                         }
;                     }
.LBB0_622:
	s_or_b64 exec, exec, s[14:15]
	s_nor_b64 s[10:11], s[12:13], s[10:11]
	s_and_saveexec_b64 s[90:91], s[10:11]
	s_cbranch_execz .LBB0_626
	v_add_u32_e32 v0, v185, v130
	ds_read_b128 v[48:51], v0
	ds_read_b128 v[138:141], v0 offset:32
	ds_read_b128 v[64:67], v0 offset:5632
	ds_read_b128 v[226:229], v0 offset:5664
	ds_read_b128 v[230:233], v0 offset:64
	ds_read_b128 v[234:237], v0 offset:5696
	ds_read_b128 v[238:241], v0 offset:96
	ds_read_b128 v[242:245], v0 offset:5728
	ds_read_b128 v[246:249], v0 offset:128
	ds_read_b128 v[250:253], v0 offset:5760
	s_add_i32 s10, s74, 64
	v_cmp_gt_i32_e32 vcc, s10, v172
	s_waitcnt lgkmcnt(9)
	v_mfma_f32_32x32x16_bf16 v[48:63], v[48:51], v[80:83], 0
	s_waitcnt lgkmcnt(8)
	v_mfma_f32_32x32x16_bf16 v[48:63], v[138:141], v[84:87], v[48:63]
	s_waitcnt lgkmcnt(7)
	v_mfma_f32_32x32x16_bf16 v[64:79], v[64:67], v[80:83], 0
	s_waitcnt lgkmcnt(6)
	v_mfma_f32_32x32x16_bf16 v[64:79], v[226:229], v[84:87], v[64:79]
	s_waitcnt lgkmcnt(5)
	v_mfma_f32_32x32x16_bf16 v[48:63], v[230:233], v[88:91], v[48:63]
	s_waitcnt lgkmcnt(4)
	v_mfma_f32_32x32x16_bf16 v[64:79], v[234:237], v[88:91], v[64:79]
	s_waitcnt lgkmcnt(3)
	v_mfma_f32_32x32x16_bf16 v[48:63], v[238:241], v[92:95], v[48:63]
	s_waitcnt lgkmcnt(2)
	v_mfma_f32_32x32x16_bf16 v[64:79], v[242:245], v[92:95], v[64:79]
	s_waitcnt lgkmcnt(1)
	v_mfma_f32_32x32x16_bf16 v[48:63], v[246:249], v[104:107], v[48:63]
	s_waitcnt lgkmcnt(0)
	v_mfma_f32_32x32x16_bf16 v[64:79], v[250:253], v[104:107], v[64:79]
	s_and_saveexec_b64 s[86:87], vcc
	s_cbranch_execz .LBB0_625
	v_subrev_u32_e32 v0, 64, v188
	v_cmp_gt_i32_e64 s[70:71], 26, v0
	v_cmp_gt_i32_e64 s[72:73], 27, v0
	v_cmp_gt_i32_e64 s[68:69], 25, v0
	s_and_b64 s[70:71], s[72:73], s[70:71]
	v_cmp_gt_i32_e64 s[66:67], 24, v0
	s_and_b64 s[68:69], s[70:71], s[68:69]
	v_cmp_gt_i32_e64 s[64:65], 19, v0
	s_and_b64 s[66:67], s[68:69], s[66:67]
	v_cmp_gt_i32_e64 s[62:63], 18, v0
	s_and_b64 s[64:65], s[66:67], s[64:65]
	v_cmp_gt_i32_e64 s[60:61], 17, v0
	s_and_b64 s[62:63], s[64:65], s[62:63]
	v_cmp_gt_i32_e64 s[58:59], 16, v0
	s_and_b64 s[60:61], s[62:63], s[60:61]
	v_cmp_gt_i32_e64 s[56:57], 11, v0
	s_and_b64 s[58:59], s[60:61], s[58:59]
	v_cmp_gt_i32_e64 s[54:55], 10, v0
	s_and_b64 s[56:57], s[58:59], s[56:57]
	v_cmp_gt_i32_e64 s[52:53], 9, v0
	s_and_b64 s[54:55], s[56:57], s[54:55]
	v_cmp_gt_i32_e64 s[50:51], 8, v0
	s_and_b64 s[52:53], s[54:55], s[52:53]
	v_cmp_gt_i32_e64 s[48:49], 3, v0
	s_and_b64 s[50:51], s[52:53], s[50:51]
	v_cmp_gt_i32_e64 s[46:47], 2, v0
	s_and_b64 s[48:49], s[50:51], s[48:49]
	v_cmp_gt_i32_e64 s[44:45], 1, v0
	s_and_b64 s[46:47], s[48:49], s[46:47]
	v_cmp_gt_i32_e64 s[42:43], 0, v0
	s_and_b64 s[44:45], s[46:47], s[44:45]
	s_and_b64 s[42:43], s[44:45], s[42:43]
	v_cmp_gt_i32_e64 s[38:39], 58, v0
	v_cndmask_b32_e64 v48, v48, v207, s[42:43]
	v_cmp_gt_i32_e64 s[42:43], 59, v0
	v_cmp_gt_i32_e64 s[36:37], 57, v0
	s_and_b64 s[38:39], s[42:43], s[38:39]
	v_cmp_gt_i32_e64 s[34:35], 56, v0
	s_and_b64 s[36:37], s[38:39], s[36:37]
	v_cmp_gt_i32_e64 s[30:31], 51, v0
	s_and_b64 s[34:35], s[36:37], s[34:35]
	v_cmp_gt_i32_e64 s[28:29], 50, v0
	s_and_b64 s[30:31], s[34:35], s[30:31]
	v_cmp_gt_i32_e64 s[26:27], 49, v0
	s_and_b64 s[28:29], s[30:31], s[28:29]
	v_cmp_gt_i32_e64 s[24:25], 48, v0
	s_and_b64 s[26:27], s[28:29], s[26:27]
	v_cmp_gt_i32_e64 s[22:23], 43, v0
	s_and_b64 s[24:25], s[26:27], s[24:25]
	v_cmp_gt_i32_e64 s[20:21], 42, v0
	s_and_b64 s[22:23], s[24:25], s[22:23]
	v_cmp_gt_i32_e64 s[18:19], 41, v0
	s_and_b64 s[20:21], s[22:23], s[20:21]
	v_cmp_gt_i32_e64 s[16:17], 40, v0
	s_and_b64 s[18:19], s[20:21], s[18:19]
	v_cmp_gt_i32_e64 s[14:15], 35, v0
	s_and_b64 s[16:17], s[18:19], s[16:17]
	v_cmp_gt_i32_e64 s[12:13], 34, v0
	s_and_b64 s[14:15], s[16:17], s[14:15]
	v_cmp_gt_i32_e64 s[10:11], 33, v0
	s_and_b64 s[12:13], s[14:15], s[12:13]
	v_cmp_gt_i32_e32 vcc, 32, v0
	v_cndmask_b32_e64 v61, v61, v207, s[68:69]
	v_readlane_b32 s68, v254, 63
	s_and_b64 s[10:11], s[12:13], s[10:11]
	v_readlane_b32 s69, v255, 0
	v_cndmask_b32_e64 v79, v79, v207, s[42:43]
	v_readlane_b32 s42, v255, 17
	s_and_b64 vcc, s[10:11], vcc
	v_cndmask_b32_e64 v63, v63, v207, s[72:73]
	v_cndmask_b32_e64 v62, v62, v207, s[70:71]
	s_mov_b32 s71, 0x800000
	s_mov_b32 s70, 0x24000
	s_mov_b32 s69, 0x8000
	v_cndmask_b32_e64 v60, v60, v207, s[66:67]
	s_mov_b32 s67, 0x18000
	s_movk_i32 s66, 0x6000
	v_cndmask_b32_e64 v59, v59, v207, s[64:65]
	s_mov_b32 s65, 0x10000
	v_readlane_b32 s64, v255, 2
	v_cndmask_b32_e64 v58, v58, v207, s[62:63]
	s_movk_i32 s62, 0x1fff
	v_readlane_b32 s63, v255, 1
	v_cndmask_b32_e64 v57, v57, v207, s[60:61]
	v_readlane_b32 s61, v255, 19
	s_mov_b32 s60, 0xc32a0000
	v_cndmask_b32_e64 v56, v56, v207, s[58:59]
	v_cndmask_b32_e64 v55, v55, v207, s[56:57]
	v_cndmask_b32_e64 v54, v54, v207, s[54:55]
	v_cndmask_b32_e64 v53, v53, v207, s[52:53]
	v_cndmask_b32_e64 v52, v52, v207, s[50:51]
	v_cndmask_b32_e64 v51, v51, v207, s[48:49]
	v_cndmask_b32_e64 v50, v50, v207, s[46:47]
	v_cndmask_b32_e64 v49, v49, v207, s[44:45]
	v_readlane_b32 s43, v255, 18
	v_cndmask_b32_e64 v78, v78, v207, s[38:39]
	s_mov_b64 s[38:39], 0x1000
	v_cndmask_b32_e64 v77, v77, v207, s[36:37]
	s_mov_b32 s36, 0x358637bd
	v_cndmask_b32_e64 v76, v76, v207, s[34:35]
	v_cndmask_b32_e64 v75, v75, v207, s[30:31]
	s_mov_b32 s30, 0x3a800000
	v_cndmask_b32_e64 v74, v74, v207, s[28:29]
	v_cndmask_b32_e64 v73, v73, v207, s[26:27]
	v_readlane_b32 s26, v255, 21
	v_cndmask_b32_e64 v72, v72, v207, s[24:25]
	v_cndmask_b32_e64 v71, v71, v207, s[22:23]
	v_cndmask_b32_e64 v70, v70, v207, s[20:21]
	v_cndmask_b32_e64 v69, v69, v207, s[18:19]
	v_cndmask_b32_e64 v68, v68, v207, s[16:17]
	v_cndmask_b32_e64 v67, v67, v207, s[14:15]
	v_cndmask_b32_e64 v66, v66, v207, s[12:13]
	v_cndmask_b32_e64 v65, v65, v207, s[10:11]
	v_cndmask_b32_e32 v64, v64, v207, vcc
; #define MFMA(a, b, c) __builtin_amdgcn_mfma_f32_32x32x16_bf16((a), (b), (c), 0, 0, 0)
; DI float fexp2(float x) { return __builtin_amdgcn_exp2f(x); }
; template <int TYPE>
; DI void attn_item(KargPtr p, int b, int h, int qb, unsigned char* smem) {
;     ...
;                 float mx = s0[0];
; #pragma unroll
;                 for (int i = 1; i < 16; ++i) mx = fmaxf(mx, s0[i]);
; #pragma unroll
;                 for (int i = 0; i < 16; ++i) mx = fmaxf(mx, s1[i]);
;                 mx = fmaxf(mx, __shfl_xor(mx, 32));
;                 const float mnew = fmaxf(m, mx);
;                 const float alpha = fexp2(m - mnew);
;                 m = mnew;
;                 float ps = 0.f;
; #pragma unroll
;                 for (int i = 0; i < 16; i += 2) {
;                     const f32x2_t mm = {mnew, mnew};
;                     const f32x2_t d0 = (f32x2_t){s0[i], s0[i + 1]} - mm, d1 = (f32x2_t){s1[i], s1[i + 1]} - mm;
;                     s0[i] = fexp2(d0[0]); s0[i + 1] = fexp2(d0[1]); s1[i] = fexp2(d1[0]); s1[i + 1] = fexp2(d1[1]);
;                     ps += (s0[i] + s0[i + 1]) + (s1[i] + s1[i + 1]);
;                 }
;                 lsum = lsum * alpha + ps;
; #pragma unroll
;                 for (int i = 0; i < 16; ++i) { o0[i] *= alpha; o1[i] *= alpha; }
;     ...
; #pragma unroll
;             for (int s2 = 0; s2 < 2; ++s2) {
;                 unsigned pk0[4], pk1[4];
; #pragma unroll
;                 for (int j = 0; j < 4; ++j) { pk0[j] = pack_bf16(s0[8 * s2 + 2 * j], s0[8 * s2 + 2 * j + 1]); pk1[j] = pack_bf16(s1[8 * s2 + 2 * j], s1[8 * s2 + 2 * j + 1]); }
;                 const uint4 u0 = make_uint4(pk0[0], pk0[1], pk0[2], pk0[3]), u1 = make_uint4(pk1[0], pk1[1], pk1[2], pk1[3]);
;                 const bf16x8 pf0 = __builtin_bit_cast(bf16x8, u0), pf1 = __builtin_bit_cast(bf16x8, u1);
;                 const bf16x8 v00 = *(const bf16x8*)(vb + r * VROWB + (16 * s2 + 8 * hh) * 2);
;                 const bf16x8 v01 = *(const bf16x8*)(vb + (32 + r) * VROWB + (16 * s2 + 8 * hh) * 2);
;                 const bf16x8 v10 = *(const bf16x8*)(vb + r * VROWB + (32 + 16 * s2 + 8 * hh) * 2);
;                 const bf16x8 v11 = *(const bf16x8*)(vb + (32 + r) * VROWB + (32 + 16 * s2 + 8 * hh) * 2);
;                 o0 = MFMA(v00, pf0, o0); o1 = MFMA(v01, pf0, o1);
;                 o0 = MFMA(v10, pf1, o0); o1 = MFMA(v11, pf1, o1);
;             }
.LBB0_625:
	s_or_b64 exec, exec, s[86:87]
	s_nop 5
	v_max_f32_e32 v0, v49, v49
	v_max_f32_e32 v1, v48, v48
	v_max_f32_e32 v0, v1, v0
	v_max3_f32 v0, v0, v50, v51
	v_max3_f32 v0, v0, v52, v53
	v_max3_f32 v0, v0, v54, v55
	v_max3_f32 v0, v0, v56, v57
	v_max3_f32 v0, v0, v58, v59
	v_max3_f32 v0, v0, v60, v61
	v_max3_f32 v0, v0, v62, v63
	v_max3_f32 v0, v0, v64, v65
	v_max3_f32 v0, v0, v66, v67
	v_max3_f32 v0, v0, v68, v69
	v_max3_f32 v0, v0, v70, v71
	v_max3_f32 v0, v0, v72, v73
	v_max3_f32 v0, v0, v74, v75
	v_max3_f32 v0, v0, v76, v77
	v_max3_f32 v0, v0, v78, v79
	v_mov_b32_e32 v1, v0
	v_mov_b32_e32 v225, v0
	s_nop 1
	v_permlane32_swap_b32_e32 v1, v225
	v_max3_f32 v0, v160, v1, v225
	v_pk_add_f32 v[48:49], v[48:49], v[0:1] op_sel_hi:[1,0] neg_lo:[0,1] neg_hi:[0,1]
	v_pk_add_f32 v[64:65], v[64:65], v[0:1] op_sel_hi:[1,0] neg_lo:[0,1] neg_hi:[0,1]
	v_exp_f32_e32 v161, v48
	v_exp_f32_e32 v165, v49
	v_pk_add_f32 v[48:49], v[50:51], v[0:1] op_sel_hi:[1,0] neg_lo:[0,1] neg_hi:[0,1]
	v_pk_add_f32 v[50:51], v[66:67], v[0:1] op_sel_hi:[1,0] neg_lo:[0,1] neg_hi:[0,1]
	v_sub_f32_e32 v2, v160, v0
	v_exp_f32_e32 v163, v64
	v_exp_f32_e32 v167, v65
	v_exp_f32_e32 v160, v48
	v_exp_f32_e32 v164, v49
	v_exp_f32_e32 v162, v50
	v_exp_f32_e32 v166, v51
	v_exp_f32_e32 v2, v2
	v_pk_add_f32 v[48:49], v[164:165], v[160:161]
	v_pk_add_f32 v[50:51], v[166:167], v[162:163]
	s_nop 0
	v_pk_add_f32 v[48:49], v[50:51], v[48:49]
	v_pk_mul_f32 v[46:47], v[46:47], v[2:3] op_sel_hi:[1,0]
	v_add_f32_e32 v1, 0, v49
	v_pk_add_f32 v[50:51], v[52:53], v[0:1] op_sel_hi:[1,0] neg_lo:[0,1] neg_hi:[0,1]
	v_pk_add_f32 v[52:53], v[68:69], v[0:1] op_sel_hi:[1,0] neg_lo:[0,1] neg_hi:[0,1]
	v_exp_f32_e32 v169, v50
	v_exp_f32_e32 v171, v51
	v_exp_f32_e32 v168, v52
	v_exp_f32_e32 v170, v53
	v_pk_add_f32 v[52:53], v[54:55], v[0:1] op_sel_hi:[1,0] neg_lo:[0,1] neg_hi:[0,1]
	v_pk_add_f32 v[54:55], v[70:71], v[0:1] op_sel_hi:[1,0] neg_lo:[0,1] neg_hi:[0,1]
	v_exp_f32_e32 v138, v52
	v_pk_add_f32 v[50:51], v[170:171], v[168:169]
	v_exp_f32_e32 v139, v53
	v_pk_add_f32 v[50:51], v[50:51], v[50:51] op_sel_hi:[0,1]
	v_exp_f32_e32 v140, v54
	v_exp_f32_e32 v141, v55
	v_pk_add_f32 v[56:57], v[56:57], v[0:1] op_sel_hi:[1,0] neg_lo:[0,1] neg_hi:[0,1]
	v_pk_add_f32 v[64:65], v[72:73], v[0:1] op_sel_hi:[1,0] neg_lo:[0,1] neg_hi:[0,1]
	v_add_f32_e32 v49, v48, v1
	v_exp_f32_e32 v48, v56
	v_exp_f32_e32 v50, v57
	v_exp_f32_e32 v52, v64
	v_exp_f32_e32 v54, v65
	v_add_f32_e32 v53, v139, v138
	v_add_f32_e32 v55, v141, v140
	v_pk_add_f32 v[56:57], v[50:51], v[48:49]
	v_pk_add_f32 v[64:65], v[54:55], v[52:53]
	v_pk_add_f32 v[66:67], v[74:75], v[0:1] op_sel_hi:[1,0] neg_lo:[0,1] neg_hi:[0,1]
	v_pk_add_f32 v[56:57], v[64:65], v[56:57]
	v_pk_add_f32 v[64:65], v[58:59], v[0:1] op_sel_hi:[1,0] neg_lo:[0,1] neg_hi:[0,1]
	v_exp_f32_e32 v58, v66
	v_exp_f32_e32 v59, v64
	v_exp_f32_e32 v65, v65
	v_exp_f32_e32 v64, v67
	v_pk_add_f32 v[60:61], v[60:61], v[0:1] op_sel_hi:[1,0] neg_lo:[0,1] neg_hi:[0,1]
	v_pk_add_f32 v[68:69], v[76:77], v[0:1] op_sel_hi:[1,0] neg_lo:[0,1] neg_hi:[0,1]
	v_pk_add_f32 v[56:57], v[56:57], v[56:57] op_sel_hi:[0,1]
	v_pk_add_f32 v[66:67], v[64:65], v[58:59]
	v_exp_f32_e32 v51, v60
	v_pk_add_f32 v[66:67], v[66:67], v[66:67] op_sel_hi:[0,1]
	v_exp_f32_e32 v55, v61
	v_exp_f32_e32 v146, v68
	v_exp_f32_e32 v147, v69
	v_pk_add_f32 v[62:63], v[62:63], v[0:1] op_sel_hi:[1,0] neg_lo:[0,1] neg_hi:[0,1]
	v_pk_add_f32 v[70:71], v[78:79], v[0:1] op_sel_hi:[1,0] neg_lo:[0,1] neg_hi:[0,1]
	v_exp_f32_e32 v56, v62
	v_exp_f32_e32 v66, v63
	v_exp_f32_e32 v60, v70
	v_exp_f32_e32 v68, v71
	v_add_f32_e32 v61, v55, v51
	v_add_f32_e32 v69, v147, v146
	v_pk_add_f32 v[62:63], v[66:67], v[56:57]
	v_pk_add_f32 v[70:71], v[68:69], v[60:61]
	v_pk_mul_f32 v[44:45], v[44:45], v[2:3] op_sel_hi:[1,0]
	v_pk_add_f32 v[62:63], v[70:71], v[62:63]
	v_pk_mul_f32 v[42:43], v[42:43], v[2:3] op_sel_hi:[1,0]
	v_add_f32_e32 v1, v62, v63
	v_fmac_f32_e32 v1, v191, v2
	v_pk_mul_f32 v[40:41], v[40:41], v[2:3] op_sel_hi:[1,0]
	v_pk_mul_f32 v[38:39], v[38:39], v[2:3] op_sel_hi:[1,0]
	v_pk_mul_f32 v[36:37], v[36:37], v[2:3] op_sel_hi:[1,0]
	v_pk_mul_f32 v[34:35], v[34:35], v[2:3] op_sel_hi:[1,0]
	v_pk_mul_f32 v[32:33], v[32:33], v[2:3] op_sel_hi:[1,0]
	v_pk_mul_f32 v[30:31], v[30:31], v[2:3] op_sel_hi:[1,0]
	v_pk_mul_f32 v[28:29], v[28:29], v[2:3] op_sel_hi:[1,0]
	v_pk_mul_f32 v[26:27], v[26:27], v[2:3] op_sel_hi:[1,0]
	v_pk_mul_f32 v[24:25], v[24:25], v[2:3] op_sel_hi:[1,0]
	v_pk_mul_f32 v[22:23], v[22:23], v[2:3] op_sel_hi:[1,0]
	v_pk_mul_f32 v[20:21], v[20:21], v[2:3] op_sel_hi:[1,0]
	v_pk_mul_f32 v[18:19], v[18:19], v[2:3] op_sel_hi:[1,0]
	v_pk_mul_f32 v[16:17], v[16:17], v[2:3] op_sel_hi:[1,0]
	v_add_u32_e32 v2, v186, v130
	v_cvt_pk_bf16_f32 v70, v161, v165
	v_cvt_pk_bf16_f32 v74, v163, v167
	v_cvt_pk_bf16_f32 v71, v160, v164
	v_cvt_pk_bf16_f32 v75, v162, v166
	v_cvt_pk_bf16_f32 v73, v138, v139
	v_cvt_pk_bf16_f32 v77, v140, v141
	ds_read_b128 v[138:141], v2 offset:15872
	ds_read_b128 v[142:145], v2 offset:11328
	ds_read_b128 v[150:153], v2 offset:15936
	ds_read_b128 v[160:163], v2 offset:11264
	ds_read_b128 v[164:167], v2 offset:11296
	v_cvt_pk_bf16_f32 v72, v169, v171
	v_cvt_pk_bf16_f32 v76, v168, v170
	v_cvt_pk_bf16_f32 v48, v48, v50
	s_waitcnt lgkmcnt(1)
	v_mfma_f32_32x32x16_bf16 v[32:47], v[160:163], v[70:73], v[32:47]
	v_cvt_pk_bf16_f32 v49, v59, v65
	v_cvt_pk_bf16_f32 v53, v58, v64
	v_cvt_pk_bf16_f32 v50, v51, v55
	v_cvt_pk_bf16_f32 v51, v56, v66
	v_cvt_pk_bf16_f32 v55, v60, v68
	ds_read_b128 v[56:59], v2 offset:15904
	ds_read_b128 v[60:63], v2 offset:11360
	ds_read_b128 v[64:67], v2 offset:15968
	v_cvt_pk_bf16_f32 v52, v52, v54
	v_mfma_f32_32x32x16_bf16 v[16:31], v[138:141], v[70:73], v[16:31]
	v_cvt_pk_bf16_f32 v54, v146, v147
	v_mov_b32_e32 v191, v1
	v_mov_b32_e32 v160, v0
	v_mfma_f32_32x32x16_bf16 v[32:47], v[142:145], v[74:77], v[32:47]
	v_mfma_f32_32x32x16_bf16 v[16:31], v[150:153], v[74:77], v[16:31]
	s_waitcnt lgkmcnt(3)
	v_mfma_f32_32x32x16_bf16 v[32:47], v[164:167], v[48:51], v[32:47]
	s_waitcnt lgkmcnt(2)
	v_mfma_f32_32x32x16_bf16 v[16:31], v[56:59], v[48:51], v[16:31]
	s_waitcnt lgkmcnt(1)
	v_mfma_f32_32x32x16_bf16 v[32:47], v[60:63], v[52:55], v[32:47]
	s_waitcnt lgkmcnt(0)
	v_mfma_f32_32x32x16_bf16 v[16:31], v[64:67], v[52:55], v[16:31]
